# S5 full tile: the two constant multiplies feeding exp2 in gelu_tanh (-1.5957691 then log2 e) merged into one f32 constant (4 fewer VALU per tile per wave; the S5 tile is issue-bound)
# speedup vs baseline: 1.0020x; 1.0020x over previous
.LBB0_919:
	s_cmp_lt_u32 s36, s101
	s_cbranch_scc1 .Ls5_state_only
	ds_read_b128 v[174:177], v166
	ds_read_b128 v[178:181], v166 offset:64
	ds_read_b128 v[182:185], v166 offset:128
	ds_read_b128 v[186:189], v166 offset:192
	s_and_b32 s38, s37, 1
	s_waitcnt lgkmcnt(3)
	v_mfma_f32_16x16x32_bf16 v[64:67], v[174:177], v[20:23], v[64:67]
	s_xor_b32 s39, s38, 1
	s_mulk_i32 s39, 0x1100
	s_waitcnt lgkmcnt(1)
	v_mfma_f32_16x16x32_bf16 v[190:193], v[182:185], v[28:31], 0
	v_mfma_f32_16x16x32_bf16 v[64:67], v[178:181], v[24:27], v[64:67]
	s_waitcnt lgkmcnt(0)
	v_mfma_f32_16x16x32_bf16 v[190:193], v[186:189], v[32:35], v[190:193]
	s_nop 7
	v_pk_add_f32 v[200:201], v[64:65], v[190:191]
	v_add_u32_e32 v64, s39, v117
	v_pk_add_f32 v[198:199], v[66:67], v[192:193]
	v_cvt_pk_bf16_f32 v65, v200, s0
	v_add_u32_e32 v66, v64, v124
	ds_write_b16 v66, v65 offset:59392
	v_cvt_pk_bf16_f32 v65, v201, s0
	v_add_u32_e32 v64, v64, v125
	ds_write_b16 v64, v65 offset:59392
	v_cvt_pk_bf16_f32 v65, v198, s0
	ds_write_b16 v64, v65 offset:59664
	v_cvt_pk_bf16_f32 v65, v199, s0
	ds_write_b16 v64, v65 offset:59936
	s_mulk_i32 s38, 0x1100
	v_add_u32_e32 v167, s38, v118
	v_mfma_f32_16x16x32_bf16 v[64:67], v[174:177], v[44:47], 0
	ds_read_b128 v[174:177], v167 offset:59392
	v_mfma_f32_16x16x32_bf16 v[64:67], v[178:181], v[40:43], v[64:67]
	ds_read_b128 v[178:181], v167 offset:59456
	ds_read_b128 v[190:193], v167 offset:59520
	ds_read_b128 v[194:197], v167 offset:59584
	v_mfma_f32_16x16x32_bf16 v[64:67], v[182:185], v[36:39], v[64:67]
	s_add_i32 s37, s37, 1
	v_add_u32_e32 v166, 0x1100, v166
	s_waitcnt lgkmcnt(3)
	v_mfma_f32_16x16x32_bf16 v[174:177], v[174:177], v[4:7], 0
	s_waitcnt lgkmcnt(2)
	v_mfma_f32_16x16x32_bf16 v[174:177], v[178:181], v[8:11], v[174:177]
	v_mov_b32_dpp v182, v200 quad_perm:[1,0,3,2] row_mask:0xf bank_mask:0xf
	v_mov_b32_dpp v184, v198 quad_perm:[1,0,3,2] row_mask:0xf bank_mask:0xf
	v_mov_b32_dpp v185, v199 quad_perm:[1,0,3,2] row_mask:0xf bank_mask:0xf
	s_waitcnt lgkmcnt(1)
	v_mfma_f32_16x16x32_bf16 v[174:177], v[190:193], v[12:15], v[174:177]
	v_mov_b32_dpp v183, v201 quad_perm:[1,0,3,2] row_mask:0xf bank_mask:0xf
	s_waitcnt lgkmcnt(0)
	v_pk_mul_f32 v[184:185], v[80:81], v[184:185]
	v_mfma_f32_16x16x32_bf16 v[174:177], v[194:197], v[16:19], v[174:177]
	s_waitcnt lgkmcnt(0)
	v_pk_mul_f32 v[182:183], v[68:69], v[182:183]
	v_mfma_f32_16x16x32_bf16 v[64:67], v[186:189], v[0:3], v[64:67]
	s_nop 7
	v_add_f32_e32 v64, v174, v64
	v_mul_f32_e32 v167, 0x3d372713, v64
	v_mul_f32_e32 v167, v64, v167
	v_fma_f32 v167, v64, v167, v64
	v_add_f32_e32 v169, v175, v65
	v_mul_f32_e32 v65, 0xc0135761, v167
	v_mul_f32_e32 v167, 0x3d372713, v169
	v_mul_f32_e32 v167, v169, v167
	v_fma_f32 v167, v169, v167, v169
	v_exp_f32_e32 v65, v65
	v_mul_f32_e32 v167, 0xc0135761, v167
	v_exp_f32_e32 v167, v167
	v_add_f32_e32 v66, v176, v66
	v_mul_f32_e32 v175, 0x3d372713, v66
	v_add_f32_e32 v65, 1.0, v65
	v_mul_f32_e32 v175, v66, v175
	v_rcp_f32_e32 v65, v65
	v_fma_f32 v175, v66, v175, v66
	v_add_f32_e32 v167, 1.0, v167
	v_mul_f32_e32 v175, 0xc0135761, v175
	v_rcp_f32_e32 v167, v167
	v_exp_f32_e32 v175, v175
	v_mul_f32_e32 v64, v64, v65
	v_cvt_pk_bf16_f32 v174, v64, s0
	v_lshl_add_u64 v[64:65], v[88:89], 0, s[2:3]
	global_store_short v[64:65], v174, off
	v_mul_f32_e32 v64, v169, v167
	v_cvt_pk_bf16_f32 v167, v64, s0
	v_add_f32_e32 v64, 1.0, v175
	v_add_f32_e32 v67, v177, v67
	v_rcp_f32_e32 v169, v64
	v_mul_f32_e32 v64, 0x3d372713, v67
	v_mul_f32_e32 v64, v67, v64
	v_fma_f32 v64, v67, v64, v67
	v_mul_f32_e32 v64, 0xc0135761, v64
	v_exp_f32_e32 v174, v64
	v_lshl_add_u64 v[64:65], v[86:87], 0, s[2:3]
	global_store_short v[64:65], v167, off
	v_mul_f32_e32 v64, v66, v169
	v_add_f32_e32 v65, 1.0, v174
	v_rcp_f32_e32 v66, v65
	v_cvt_pk_bf16_f32 v167, v64, s0
	v_lshl_add_u64 v[64:65], v[84:85], 0, s[2:3]
	global_store_short v[64:65], v167, off
	v_mul_f32_e32 v64, v67, v66
	v_cvt_pk_bf16_f32 v66, v64, s0
	v_lshl_add_u64 v[64:65], v[82:83], 0, s[2:3]
	s_add_u32 s2, s2, 0x4000
	s_addc_u32 s3, s3, 0
	global_store_short v[64:65], v66, off
	v_pk_fma_f32 v[66:67], v[78:79], v[198:199], v[184:185]
	v_pk_fma_f32 v[64:65], v[100:101], v[200:201], v[182:183]
	s_cmp_eq_u32 s2, 0x10000
	s_cbranch_scc1 .LBB0_917
